# layer1-3 weight transposes deferred from phase 0 to end of attention L0 phase; sw_tasks moved to end of out-proj L0 phase
# baseline (speedup 1.0000x reference)
.LBB0_22:
	s_sub_u32 s14, s97, 0x2c0
	s_cmp_lt_u32 s14, 0x550
	s_cbranch_scc1 .LBB0_21
	s_sub_u32 s14, s97, 0x890
	s_cmp_lt_u32 s14, 0x180
	s_cbranch_scc1 .LBB0_21
	s_cmpk_gt_i32 s97, 0x17f
	s_mov_b64 s[14:15], -1
	s_barrier
	s_cbranch_scc0 .LBB0_114
	s_cmpk_gt_u32 s97, 0xb8f
	s_cbranch_scc0 .LBB0_48
	s_cmpk_lg_i32 s97, 0xe90
	s_cbranch_scc0 .LBB0_26
	s_cmpk_lt_u32 s97, 0xc10
	s_cselect_b64 s[0:1], -1, 0
	s_cmpk_lt_u32 s97, 0xc90
	s_cselect_b64 s[14:15], -1, 0
	s_and_b64 s[14:15], s[14:15], exec
	s_movk_i32 s2, 0xf3f0
	s_mov_b32 s14, 0xf882100
	s_cselect_b32 s2, s2, 0xfffff370
	s_cselect_b32 s16, 56, 32
	s_cselect_b32 s17, s14, 0xd440000
	s_and_b64 s[14:15], s[0:1], exec
	s_cselect_b32 s14, 16, s16
	v_readlane_b32 s18, v253, 0
	s_cselect_b32 s2, 0xfffff470, s2
	v_readlane_b32 s19, v253, 1
	s_add_u32 s14, s18, s14
	s_addc_u32 s15, s19, 0
	s_and_b64 s[0:1], s[0:1], exec
	s_cselect_b32 s0, 0xf682100, s17
	s_load_dwordx2 s[14:15], s[14:15], 0x0
	s_add_u32 s0, s40, s0
	s_addc_u32 s1, s41, 0
	s_add_i32 s16, s97, s2
	s_mov_b32 s17, s36
	s_lshl_b64 s[16:17], s[16:17], 12
	v_lshl_add_u64 v[8:9], s[16:17], 0, v[144:145]
	s_waitcnt lgkmcnt(0)
	v_lshl_add_u64 v[10:11], v[8:9], 2, s[14:15]
	global_load_dwordx4 v[0:3], v[10:11], off nt
	global_load_dwordx4 v[4:7], v[10:11], off offset:16 nt
	v_lshl_add_u64 v[8:9], v[8:9], 1, s[0:1]
	s_mov_b64 s[14:15], 0
	s_waitcnt vmcnt(1)
	v_cvt_pk_bf16_f32 v0, v0, v1
	v_cvt_pk_bf16_f32 v1, v2, v3
	s_waitcnt vmcnt(0)
	v_cvt_pk_bf16_f32 v2, v4, v5
	v_cvt_pk_bf16_f32 v3, v6, v7
	global_store_dwordx4 v[8:9], v[0:3], off
	global_load_dwordx4 v[0:3], v[10:11], off offset:32 nt
	s_nop 0
	global_load_dwordx4 v[4:7], v[10:11], off offset:48 nt
	s_waitcnt vmcnt(1)
	v_cvt_pk_bf16_f32 v0, v0, v1
	v_cvt_pk_bf16_f32 v1, v2, v3
	s_waitcnt vmcnt(0)
	v_cvt_pk_bf16_f32 v2, v4, v5
	v_cvt_pk_bf16_f32 v3, v6, v7
	global_store_dwordx4 v[8:9], v[0:3], off offset:16

.LBB0_200:
	s_or_b64 exec, exec, s[6:7]
	s_movk_i32 s0, 0x544
	v_cmp_gt_i32_e32 vcc, s0, v150
	v_and_b32_e32 v156, 63, v146
	s_and_saveexec_b64 s[8:9], vcc
	s_cbranch_execz .LBB0_231
.LBB0_231:
	s_or_b64 exec, exec, s[8:9]
	s_waitcnt vmcnt(0)
	s_waitcnt lgkmcnt(0)
	s_barrier
	s_mov_b64 s[6:7], exec
	v_readlane_b32 s0, v253, 2
	v_readlane_b32 s1, v253, 3
	s_and_b64 s[0:1], s[6:7], s[0:1]
	s_mov_b64 exec, s[0:1]
	s_cbranch_execz .LBB0_283
	v_mov_b32_e32 v0, 0x13000
	s_waitcnt vmcnt(0) expcnt(0) lgkmcnt(0)
	ds_read_b32 v2, v0
	v_mov_b32_e32 v0, 0x13004
	ds_read_b32 v0, v0
	s_waitcnt lgkmcnt(1)
	v_cmp_ne_u32_e32 vcc, 0, v2
	s_cbranch_vccnz .LBB0_247
	v_readlane_b32 s2, v253, 0
	v_readlane_b32 s3, v253, 1
	s_load_dwordx2 s[0:1], s[2:3], 0x168
	v_mov_b32_e32 v16, 0
	s_waitcnt lgkmcnt(0)
	s_mov_b64 s[2:3], s[0:1]
	v_readlane_b32 s0, v253, 4
	s_mul_i32 s0, s3, s0
	s_mul_i32 s0, s0, s2
	v_readlane_b32 s2, v253, 10
	v_readlane_b32 s3, v253, 11
	s_add_u32 s8, s2, 0xf67e300
	s_addc_u32 s9, s3, 0
	s_add_u32 s10, s2, 0xf67e500
	s_addc_u32 s11, s3, 0
	s_add_u32 s12, s2, 0xf67e600
	s_addc_u32 s13, s3, 0
	s_add_u32 s14, s2, 0xf67e700
	s_addc_u32 s15, s3, 0
	s_add_u32 s16, s2, 0xf67e800
	s_addc_u32 s17, s3, 0
	s_add_u32 s18, s2, 0xf67e900
	s_addc_u32 s19, s3, 0
	s_add_u32 s20, s2, 0xf67ea00
	s_addc_u32 s21, s3, 0
	s_add_u32 s22, s2, 0xf67eb00
	s_addc_u32 s23, s3, 0
	s_add_u32 s24, s2, 0xf67ec00
	s_addc_u32 s25, s3, 0
	s_add_u32 s26, s2, 0xf67ed00
	s_addc_u32 s27, s3, 0
	s_add_u32 s28, s2, 0xf67ee00
	s_addc_u32 s29, s3, 0
	s_add_u32 s30, s2, 0xf67ef00
	s_addc_u32 s31, s3, 0
	s_add_u32 s34, s2, 0xf67f000
	s_addc_u32 s35, s3, 0
	s_add_u32 s36, s2, 0xf67f100
	s_addc_u32 s37, s3, 0
	s_add_u32 s38, s2, 0xf67f200
	s_addc_u32 s39, s3, 0
	s_add_u32 s40, s2, 0xf67f300
	s_addc_u32 s41, s3, 0
	s_add_u32 s42, s2, 0xf67f400
	s_addc_u32 s43, s3, 0
	s_mov_b32 s1, 1
	s_branch .LBB0_235

.LBB0_407:
	v_readlane_b32 s2, v253, 0
	v_readlane_b32 s3, v253, 1
	s_load_dwordx2 s[4:5], s[2:3], 0x160
	s_load_dwordx2 s[6:7], s[2:3], 0x168
	v_lshrrev_b32_e32 v60, 4, v146
	v_and_b32_e32 v60, 15, v60
	v_and_b32_e32 v61, 15, v146
	v_lshlrev_b32_e32 v61, 2, v61
	v_lshrrev_b32_e32 v62, 3, v146
	v_and_b32_e32 v62, 31, v62
	v_and_b32_e32 v63, 7, v146
	v_mul_u32_u24_e32 v64, 65, v60
	v_add_u32_e32 v64, v64, v61
	v_lshlrev_b32_e32 v64, 2, v64
	v_mul_u32_u24_e32 v65, 0x208, v63
	v_add_u32_e32 v65, v65, v62
	v_lshlrev_b32_e32 v65, 2, v65
	s_mov_b32 s1, s69
	s_waitcnt lgkmcnt(0)
	s_cmp_lt_u32 s1, 0x6d0
	s_cbranch_scc0 .Ltr_done
.Ltr_task:
	s_cmp_lt_u32 s1, 0x200
	s_cbranch_scc0 .Ltr_d2
	s_mov_b32 s10, 0x1000
	s_movk_i32 s12, 0xa0
	s_mov_b32 s13, 0x7700000
	s_lshr_b32 s15, s1, 5
	s_and_b32 s14, s1, 31
	s_branch .Ltr_dd
.Ltr_d2:
	s_cmp_lt_u32 s1, 0x410
	s_cbranch_scc0 .Ltr_d3
	s_sub_u32 s8, s1, 0x200
	s_mov_b32 s10, 0x1020
	s_movk_i32 s12, 0xf0
	s_mov_b32 s13, 0x7f00000
	s_mul_i32 s15, s8, 0x7c2
	s_lshr_b32 s15, s15, 16
	s_mul_i32 s14, s15, 33
	s_sub_u32 s14, s8, s14
	s_branch .Ltr_dd
.Ltr_d3:
	s_cmp_lt_u32 s1, 0x550
	s_cbranch_scc0 .Ltr_d4
	s_sub_u32 s8, s1, 0x410
	s_mov_b32 s10, 0xa00
	s_movk_i32 s12, 0x138
	s_mov_b32 s13, 0x8740000
	s_mul_i32 s15, s8, 0xccd
	s_lshr_b32 s15, s15, 16
	s_mul_i32 s14, s15, 20
	s_sub_u32 s14, s8, s14
	s_branch .Ltr_dd
.Ltr_d4:
	s_sub_u32 s8, s1, 0x4d0
	s_lshr_b32 s9, s8, 7
	s_and_b32 s8, s8, 0x7f
	s_mov_b32 s10, 0x400
	s_lshl_b32 s13, s9, 21
	s_add_u32 s13, s13, 0x8c40000
	s_movk_i32 s12, 0xa8
	s_cmp_eq_u32 s9, 2
	s_cselect_b32 s12, 0xf8, s12
	s_cmp_eq_u32 s9, 3
	s_cselect_b32 s12, 0x140, s12
	s_lshr_b32 s15, s8, 3
	s_and_b32 s14, s8, 7
.Ltr_dd:
	s_load_dwordx2 s[16:17], s[2:3], s12
	s_lshl_b32 s14, s14, 7
	s_lshl_b32 s18, s15, 6
	v_add_u32_e32 v0, s18, v60
	v_mul_lo_u32 v0, v0, s10
	v_add_u32_e32 v1, s14, v61
	v_cmp_gt_u32_e64 s[24:25], s10, v1
	v_add_u32_e32 v2, 64, v1
	v_cmp_gt_u32_e64 s[26:27], s10, v2
	v_add_u32_e32 v2, v0, v1
	v_lshlrev_b32_e32 v2, 2, v2
	v_add_u32_e32 v3, 0x100, v2
	s_lshl_b32 s19, s10, 6
	v_mov_b32_e32 v8, 0
	v_mov_b32_e32 v9, 0
	v_mov_b32_e32 v10, 0
	v_mov_b32_e32 v11, 0
	v_mov_b32_e32 v12, 0
	v_mov_b32_e32 v13, 0
	v_mov_b32_e32 v14, 0
	v_mov_b32_e32 v15, 0
	v_mov_b32_e32 v16, 0
	v_mov_b32_e32 v17, 0
	v_mov_b32_e32 v18, 0
	v_mov_b32_e32 v19, 0
	v_mov_b32_e32 v20, 0
	v_mov_b32_e32 v21, 0
	v_mov_b32_e32 v22, 0
	v_mov_b32_e32 v23, 0
	v_mov_b32_e32 v24, 0
	v_mov_b32_e32 v25, 0
	v_mov_b32_e32 v26, 0
	v_mov_b32_e32 v27, 0
	v_mov_b32_e32 v28, 0
	v_mov_b32_e32 v29, 0
	v_mov_b32_e32 v30, 0
	v_mov_b32_e32 v31, 0
	v_mov_b32_e32 v32, 0
	v_mov_b32_e32 v33, 0
	v_mov_b32_e32 v34, 0
	v_mov_b32_e32 v35, 0
	v_mov_b32_e32 v36, 0
	v_mov_b32_e32 v37, 0
	v_mov_b32_e32 v38, 0
	v_mov_b32_e32 v39, 0
	s_waitcnt lgkmcnt(0)
	s_mov_b64 exec, s[24:25]
	global_load_dwordx4 v[8:11], v2, s[16:17] nt
	v_add_u32_e32 v2, s19, v2
	global_load_dwordx4 v[12:15], v2, s[16:17] nt
	v_add_u32_e32 v2, s19, v2
	global_load_dwordx4 v[16:19], v2, s[16:17] nt
	v_add_u32_e32 v2, s19, v2
	global_load_dwordx4 v[20:23], v2, s[16:17] nt
	s_mov_b64 exec, s[26:27]
	global_load_dwordx4 v[24:27], v3, s[16:17] nt
	v_add_u32_e32 v3, s19, v3
	global_load_dwordx4 v[28:31], v3, s[16:17] nt
	v_add_u32_e32 v3, s19, v3
	global_load_dwordx4 v[32:35], v3, s[16:17] nt
	v_add_u32_e32 v3, s19, v3
	global_load_dwordx4 v[36:39], v3, s[16:17] nt
	s_mov_b64 exec, -1
	v_add_u32_e32 v4, s14, v62
	v_lshlrev_b32_e32 v4, 11, v4
	v_lshl_add_u32 v4, v63, 4, v4
	s_lshl_b32 s18, s15, 7
	s_add_u32 s18, s18, s13
	v_add_u32_e32 v4, s18, v4
	v_add_u32_e32 v5, 0x10000, v4
	v_add_u32_e32 v6, 0x20000, v4
	v_add_u32_e32 v7, 0x30000, v4
	s_barrier
	s_waitcnt vmcnt(0)
	ds_write_b32 v64, v8
	ds_write_b32 v64, v9 offset:4
	ds_write_b32 v64, v10 offset:8
	ds_write_b32 v64, v11 offset:12
	ds_write_b32 v64, v12 offset:4160
	ds_write_b32 v64, v13 offset:4164
	ds_write_b32 v64, v14 offset:4168
	ds_write_b32 v64, v15 offset:4172
	ds_write_b32 v64, v16 offset:8320
	ds_write_b32 v64, v17 offset:8324
	ds_write_b32 v64, v18 offset:8328
	ds_write_b32 v64, v19 offset:8332
	ds_write_b32 v64, v20 offset:12480
	ds_write_b32 v64, v21 offset:12484
	ds_write_b32 v64, v22 offset:12488
	ds_write_b32 v64, v23 offset:12492
	ds_write_b32 v64, v24 offset:16640
	ds_write_b32 v64, v25 offset:16644
	ds_write_b32 v64, v26 offset:16648
	ds_write_b32 v64, v27 offset:16652
	ds_write_b32 v64, v28 offset:20800
	ds_write_b32 v64, v29 offset:20804
	ds_write_b32 v64, v30 offset:20808
	ds_write_b32 v64, v31 offset:20812
	ds_write_b32 v64, v32 offset:24960
	ds_write_b32 v64, v33 offset:24964
	ds_write_b32 v64, v34 offset:24968
	ds_write_b32 v64, v35 offset:24972
	ds_write_b32 v64, v36 offset:29120
	ds_write_b32 v64, v37 offset:29124
	ds_write_b32 v64, v38 offset:29128
	ds_write_b32 v64, v39 offset:29132
	s_waitcnt lgkmcnt(0)
	s_barrier
	ds_read_b32 v40, v65
	ds_read_b32 v41, v65 offset:260
	ds_read_b32 v42, v65 offset:520
	ds_read_b32 v43, v65 offset:780
	ds_read_b32 v44, v65 offset:1040
	ds_read_b32 v45, v65 offset:1300
	ds_read_b32 v46, v65 offset:1560
	ds_read_b32 v47, v65 offset:1820
	s_waitcnt lgkmcnt(0)
	v_cvt_pk_bf16_f32 v48, v40, v41
	v_cvt_pk_bf16_f32 v49, v42, v43
	v_cvt_pk_bf16_f32 v50, v44, v45
	v_cvt_pk_bf16_f32 v51, v46, v47
	global_store_dwordx4 v4, v[48:51], s[4:5]
	s_nop 1
	ds_read_b32 v40, v65 offset:128
	ds_read_b32 v41, v65 offset:388
	ds_read_b32 v42, v65 offset:648
	ds_read_b32 v43, v65 offset:908
	ds_read_b32 v44, v65 offset:1168
	ds_read_b32 v45, v65 offset:1428
	ds_read_b32 v46, v65 offset:1688
	ds_read_b32 v47, v65 offset:1948
	s_waitcnt lgkmcnt(0)
	v_cvt_pk_bf16_f32 v48, v40, v41
	v_cvt_pk_bf16_f32 v49, v42, v43
	v_cvt_pk_bf16_f32 v50, v44, v45
	v_cvt_pk_bf16_f32 v51, v46, v47
	global_store_dwordx4 v5, v[48:51], s[4:5]
	s_nop 1
	ds_read_b32 v40, v65 offset:16640
	ds_read_b32 v41, v65 offset:16900
	ds_read_b32 v42, v65 offset:17160
	ds_read_b32 v43, v65 offset:17420
	ds_read_b32 v44, v65 offset:17680
	ds_read_b32 v45, v65 offset:17940
	ds_read_b32 v46, v65 offset:18200
	ds_read_b32 v47, v65 offset:18460
	s_waitcnt lgkmcnt(0)
	v_cvt_pk_bf16_f32 v48, v40, v41
	v_cvt_pk_bf16_f32 v49, v42, v43
	v_cvt_pk_bf16_f32 v50, v44, v45
	v_cvt_pk_bf16_f32 v51, v46, v47
	global_store_dwordx4 v6, v[48:51], s[4:5]
	s_nop 1
	ds_read_b32 v40, v65 offset:16768
	ds_read_b32 v41, v65 offset:17028
	ds_read_b32 v42, v65 offset:17288
	ds_read_b32 v43, v65 offset:17548
	ds_read_b32 v44, v65 offset:17808
	ds_read_b32 v45, v65 offset:18068
	ds_read_b32 v46, v65 offset:18328
	ds_read_b32 v47, v65 offset:18588
	s_waitcnt lgkmcnt(0)
	v_cvt_pk_bf16_f32 v48, v40, v41
	v_cvt_pk_bf16_f32 v49, v42, v43
	v_cvt_pk_bf16_f32 v50, v44, v45
	v_cvt_pk_bf16_f32 v51, v46, v47
	global_store_dwordx4 v7, v[48:51], s[4:5]
	s_nop 1
	s_add_u32 s1, s1, s6
	s_cmp_lt_u32 s1, 0x6d0
	s_cbranch_scc1 .Ltr_task

.LBB0_472:
	v_mbcnt_hi_u32_b32 v140, -1, v145
	v_readlane_b32 s2, v253, 0
	v_readlane_b32 s3, v253, 1
	s_load_dwordx2 s[10:11], s[2:3], 0x168
	s_load_dwordx2 s[4:5], s[2:3], 0x160
	v_lshlrev_b32_e32 v141, 5, v140
	v_readfirstlane_b32 s1, v150
	s_waitcnt lgkmcnt(0)
	s_lshl_b32 s0, s10, 2
	s_cmp_lt_u32 s1, 0x544
	s_cbranch_scc0 .Lsw_skip

.Lsw_dec:
	s_mul_i32 s13, s10, 0x3000
	s_add_u32 s14, s4, 0xf440000
	s_addc_u32 s15, s5, 0
	s_add_u32 s14, s14, s13
	s_addc_u32 s15, s15, 0
	v_lshlrev_b32_e32 v139, 6, v140
	global_load_dwordx4 v[0:3], v139, s[14:15]
	global_load_dwordx4 v[4:7], v139, s[14:15] offset:16
	global_load_dwordx4 v[8:11], v139, s[14:15] offset:32
	global_load_dwordx4 v[12:15], v139, s[14:15] offset:48
	s_add_u32 s14, s14, 0x3000
	s_addc_u32 s15, s15, 0
	global_load_dwordx4 v[16:19], v139, s[14:15]
	global_load_dwordx4 v[20:23], v139, s[14:15] offset:16
	global_load_dwordx4 v[24:27], v139, s[14:15] offset:32
	global_load_dwordx4 v[28:31], v139, s[14:15] offset:48
	s_add_u32 s14, s14, 0x3000
	s_addc_u32 s15, s15, 0
	global_load_dwordx4 v[32:35], v139, s[14:15]
	global_load_dwordx4 v[36:39], v139, s[14:15] offset:16
	global_load_dwordx4 v[40:43], v139, s[14:15] offset:32
	global_load_dwordx4 v[44:47], v139, s[14:15] offset:48
	s_add_u32 s14, s14, 0x3000
	s_addc_u32 s15, s15, 0
	global_load_dwordx4 v[48:51], v139, s[14:15]
	global_load_dwordx4 v[52:55], v139, s[14:15] offset:16
	global_load_dwordx4 v[56:59], v139, s[14:15] offset:32
	global_load_dwordx4 v[60:63], v139, s[14:15] offset:48
	s_add_u32 s14, s14, 0x3000
	s_addc_u32 s15, s15, 0
	global_load_dwordx4 v[64:67], v139, s[14:15]
	global_load_dwordx4 v[68:71], v139, s[14:15] offset:16
	global_load_dwordx4 v[72:75], v139, s[14:15] offset:32
	global_load_dwordx4 v[76:79], v139, s[14:15] offset:48
	s_lshl_b32 s16, s11, 14
	s_add_u32 s16, s16, s12
	s_add_u32 s16, s4, s16
	s_addc_u32 s17, s5, 0
	s_mul_i32 s24, s10, 0x4200
	s_lshl_b32 s25, s11, 5
	s_add_u32 s24, s24, s25
	s_add_u32 s24, s24, 0xfaa2100
	s_add_u32 s24, s4, s24
	s_addc_u32 s25, s5, 0
	global_load_dwordx4 v[82:85], v141, s[16:17]
	global_load_dwordx4 v[86:89], v141, s[16:17] offset:16
	global_load_dwordx4 v[90:93], v141, s[16:17] offset:2048
	global_load_dwordx4 v[94:97], v141, s[16:17] offset:2064
	s_add_u32 s16, s16, 0x1000
	s_addc_u32 s17, s17, 0
	global_load_dwordx4 v[98:101], v141, s[16:17]
	global_load_dwordx4 v[102:105], v141, s[16:17] offset:16
	global_load_dwordx4 v[106:109], v141, s[16:17] offset:2048
	global_load_dwordx4 v[110:113], v141, s[16:17] offset:2064
	s_waitcnt vmcnt(4)
	v_lshlrev_b32_e32 v114, 16, v82
	v_and_b32_e32 v115, 0xffff0000, v82
	v_lshlrev_b32_e32 v116, 16, v83
	v_and_b32_e32 v117, 0xffff0000, v83
	v_lshlrev_b32_e32 v118, 16, v84
	v_and_b32_e32 v119, 0xffff0000, v84
	v_lshlrev_b32_e32 v120, 16, v85
	v_and_b32_e32 v121, 0xffff0000, v85
	v_lshlrev_b32_e32 v122, 16, v86
	v_and_b32_e32 v123, 0xffff0000, v86
	v_lshlrev_b32_e32 v124, 16, v87
	v_and_b32_e32 v125, 0xffff0000, v87
	v_lshlrev_b32_e32 v126, 16, v88
	v_and_b32_e32 v127, 0xffff0000, v88
	v_lshlrev_b32_e32 v128, 16, v89
	v_and_b32_e32 v129, 0xffff0000, v89
	v_fma_f32 v130, v0, v114, 0
	v_fma_f32 v131, v16, v114, 0
	v_fma_f32 v132, v32, v114, 0
	v_fma_f32 v133, v48, v114, 0
	v_fma_f32 v134, v64, v114, 0
	v_fmac_f32_e32 v130, v1, v115
	v_fmac_f32_e32 v131, v17, v115
	v_fmac_f32_e32 v132, v33, v115
	v_fmac_f32_e32 v133, v49, v115
	v_fmac_f32_e32 v134, v65, v115
	v_fmac_f32_e32 v130, v2, v116
	v_fmac_f32_e32 v131, v18, v116
	v_fmac_f32_e32 v132, v34, v116
	v_fmac_f32_e32 v133, v50, v116
	v_fmac_f32_e32 v134, v66, v116
	v_fmac_f32_e32 v130, v3, v117
	v_fmac_f32_e32 v131, v19, v117
	v_fmac_f32_e32 v132, v35, v117
	v_fmac_f32_e32 v133, v51, v117
	v_fmac_f32_e32 v134, v67, v117
	v_fmac_f32_e32 v130, v4, v118
	v_fmac_f32_e32 v131, v20, v118
	v_fmac_f32_e32 v132, v36, v118
	v_fmac_f32_e32 v133, v52, v118
	v_fmac_f32_e32 v134, v68, v118
	v_fmac_f32_e32 v130, v5, v119
	v_fmac_f32_e32 v131, v21, v119
	v_fmac_f32_e32 v132, v37, v119
	v_fmac_f32_e32 v133, v53, v119
	v_fmac_f32_e32 v134, v69, v119
	v_fmac_f32_e32 v130, v6, v120
	v_fmac_f32_e32 v131, v22, v120
	v_fmac_f32_e32 v132, v38, v120
	v_fmac_f32_e32 v133, v54, v120
	v_fmac_f32_e32 v134, v70, v120
	v_fmac_f32_e32 v130, v7, v121
	v_fmac_f32_e32 v131, v23, v121
	v_fmac_f32_e32 v132, v39, v121
	v_fmac_f32_e32 v133, v55, v121
	v_fmac_f32_e32 v134, v71, v121
	v_fmac_f32_e32 v130, v8, v122
	v_fmac_f32_e32 v131, v24, v122
	v_fmac_f32_e32 v132, v40, v122
	v_fmac_f32_e32 v133, v56, v122
	v_fmac_f32_e32 v134, v72, v122
	v_fmac_f32_e32 v130, v9, v123
	v_fmac_f32_e32 v131, v25, v123
	v_fmac_f32_e32 v132, v41, v123
	v_fmac_f32_e32 v133, v57, v123
	v_fmac_f32_e32 v134, v73, v123
	v_fmac_f32_e32 v130, v10, v124
	v_fmac_f32_e32 v131, v26, v124
	v_fmac_f32_e32 v132, v42, v124
	v_fmac_f32_e32 v133, v58, v124
	v_fmac_f32_e32 v134, v74, v124
	v_fmac_f32_e32 v130, v11, v125
	v_fmac_f32_e32 v131, v27, v125
	v_fmac_f32_e32 v132, v43, v125
	v_fmac_f32_e32 v133, v59, v125
	v_fmac_f32_e32 v134, v75, v125
	v_fmac_f32_e32 v130, v12, v126
	v_fmac_f32_e32 v131, v28, v126
	v_fmac_f32_e32 v132, v44, v126
	v_fmac_f32_e32 v133, v60, v126
	v_fmac_f32_e32 v134, v76, v126
	v_fmac_f32_e32 v130, v13, v127
	v_fmac_f32_e32 v131, v29, v127
	v_fmac_f32_e32 v132, v45, v127
	v_fmac_f32_e32 v133, v61, v127
	v_fmac_f32_e32 v134, v77, v127
	v_fmac_f32_e32 v130, v14, v128
	v_fmac_f32_e32 v131, v30, v128
	v_fmac_f32_e32 v132, v46, v128
	v_fmac_f32_e32 v133, v62, v128
	v_fmac_f32_e32 v134, v78, v128
	v_fmac_f32_e32 v130, v15, v129
	v_fmac_f32_e32 v131, v31, v129
	v_fmac_f32_e32 v132, v47, v129
	v_fmac_f32_e32 v133, v63, v129
	v_fmac_f32_e32 v134, v79, v129
	v_lshlrev_b32_e32 v114, 16, v90
	v_and_b32_e32 v115, 0xffff0000, v90
	v_lshlrev_b32_e32 v116, 16, v91
	v_and_b32_e32 v117, 0xffff0000, v91
	v_lshlrev_b32_e32 v118, 16, v92
	v_and_b32_e32 v119, 0xffff0000, v92
	v_lshlrev_b32_e32 v120, 16, v93
	v_and_b32_e32 v121, 0xffff0000, v93
	v_lshlrev_b32_e32 v122, 16, v94
	v_and_b32_e32 v123, 0xffff0000, v94
	v_lshlrev_b32_e32 v124, 16, v95
	v_and_b32_e32 v125, 0xffff0000, v95
	v_lshlrev_b32_e32 v126, 16, v96
	v_and_b32_e32 v127, 0xffff0000, v96
	v_lshlrev_b32_e32 v128, 16, v97
	v_and_b32_e32 v129, 0xffff0000, v97
	v_fma_f32 v135, v0, v114, 0
	v_fma_f32 v136, v16, v114, 0
	v_fma_f32 v137, v32, v114, 0
	v_fma_f32 v138, v48, v114, 0
	v_fma_f32 v139, v64, v114, 0
	v_fmac_f32_e32 v135, v1, v115
	v_fmac_f32_e32 v136, v17, v115
	v_fmac_f32_e32 v137, v33, v115
	v_fmac_f32_e32 v138, v49, v115
	v_fmac_f32_e32 v139, v65, v115
	v_fmac_f32_e32 v135, v2, v116
	v_fmac_f32_e32 v136, v18, v116
	v_fmac_f32_e32 v137, v34, v116
	v_fmac_f32_e32 v138, v50, v116
	v_fmac_f32_e32 v139, v66, v116
	v_fmac_f32_e32 v135, v3, v117
	v_fmac_f32_e32 v136, v19, v117
	v_fmac_f32_e32 v137, v35, v117
	v_fmac_f32_e32 v138, v51, v117
	v_fmac_f32_e32 v139, v67, v117
	v_fmac_f32_e32 v135, v4, v118
	v_fmac_f32_e32 v136, v20, v118
	v_fmac_f32_e32 v137, v36, v118
	v_fmac_f32_e32 v138, v52, v118
	v_fmac_f32_e32 v139, v68, v118
	v_fmac_f32_e32 v135, v5, v119
	v_fmac_f32_e32 v136, v21, v119
	v_fmac_f32_e32 v137, v37, v119
	v_fmac_f32_e32 v138, v53, v119
	v_fmac_f32_e32 v139, v69, v119
	v_fmac_f32_e32 v135, v6, v120
	v_fmac_f32_e32 v136, v22, v120
	v_fmac_f32_e32 v137, v38, v120
	v_fmac_f32_e32 v138, v54, v120
	v_fmac_f32_e32 v139, v70, v120
	v_fmac_f32_e32 v135, v7, v121
	v_fmac_f32_e32 v136, v23, v121
	v_fmac_f32_e32 v137, v39, v121
	v_fmac_f32_e32 v138, v55, v121
	v_fmac_f32_e32 v139, v71, v121
	v_fmac_f32_e32 v135, v8, v122
	v_fmac_f32_e32 v136, v24, v122
	v_fmac_f32_e32 v137, v40, v122
	v_fmac_f32_e32 v138, v56, v122
	v_fmac_f32_e32 v139, v72, v122
	v_fmac_f32_e32 v135, v9, v123
	v_fmac_f32_e32 v136, v25, v123
	v_fmac_f32_e32 v137, v41, v123
	v_fmac_f32_e32 v138, v57, v123
	v_fmac_f32_e32 v139, v73, v123
	v_fmac_f32_e32 v135, v10, v124
	v_fmac_f32_e32 v136, v26, v124
	v_fmac_f32_e32 v137, v42, v124
	v_fmac_f32_e32 v138, v58, v124
	v_fmac_f32_e32 v139, v74, v124
	v_fmac_f32_e32 v135, v11, v125
	v_fmac_f32_e32 v136, v27, v125
	v_fmac_f32_e32 v137, v43, v125
	v_fmac_f32_e32 v138, v59, v125
	v_fmac_f32_e32 v139, v75, v125
	v_fmac_f32_e32 v135, v12, v126
	v_fmac_f32_e32 v136, v28, v126
	v_fmac_f32_e32 v137, v44, v126
	v_fmac_f32_e32 v138, v60, v126
	v_fmac_f32_e32 v139, v76, v126
	v_fmac_f32_e32 v135, v13, v127
	v_fmac_f32_e32 v136, v29, v127
	v_fmac_f32_e32 v137, v45, v127
	v_fmac_f32_e32 v138, v61, v127
	v_fmac_f32_e32 v139, v77, v127
	v_fmac_f32_e32 v135, v14, v128
	v_fmac_f32_e32 v136, v30, v128
	v_fmac_f32_e32 v137, v46, v128
	v_fmac_f32_e32 v138, v62, v128
	v_fmac_f32_e32 v139, v78, v128
	v_fmac_f32_e32 v135, v15, v129
	v_fmac_f32_e32 v136, v31, v129
	v_fmac_f32_e32 v137, v47, v129
	v_fmac_f32_e32 v138, v63, v129
	v_fmac_f32_e32 v139, v79, v129
	v_xor_b32_e32 v124, 32, v140
	v_lshlrev_b32_e32 v124, 2, v124
	v_xor_b32_e32 v125, 16, v140
	v_lshlrev_b32_e32 v125, 2, v125
	v_xor_b32_e32 v126, 8, v140
	v_lshlrev_b32_e32 v126, 2, v126
	v_xor_b32_e32 v127, 4, v140
	v_lshlrev_b32_e32 v127, 2, v127
	v_xor_b32_e32 v128, 2, v140
	v_lshlrev_b32_e32 v128, 2, v128
	v_xor_b32_e32 v129, 1, v140
	v_lshlrev_b32_e32 v129, 2, v129
	ds_bpermute_b32 v114, v124, v130
	ds_bpermute_b32 v115, v124, v131
	ds_bpermute_b32 v116, v124, v132
	ds_bpermute_b32 v117, v124, v133
	ds_bpermute_b32 v118, v124, v134
	ds_bpermute_b32 v119, v124, v135
	ds_bpermute_b32 v120, v124, v136
	ds_bpermute_b32 v121, v124, v137
	ds_bpermute_b32 v122, v124, v138
	ds_bpermute_b32 v123, v124, v139
	s_waitcnt lgkmcnt(0)
	v_add_f32_e32 v130, v130, v114
	v_add_f32_e32 v131, v131, v115
	v_add_f32_e32 v132, v132, v116
	v_add_f32_e32 v133, v133, v117
	v_add_f32_e32 v134, v134, v118
	v_add_f32_e32 v135, v135, v119
	v_add_f32_e32 v136, v136, v120
	v_add_f32_e32 v137, v137, v121
	v_add_f32_e32 v138, v138, v122
	v_add_f32_e32 v139, v139, v123
	ds_bpermute_b32 v114, v125, v130
	ds_bpermute_b32 v115, v125, v131
	ds_bpermute_b32 v116, v125, v132
	ds_bpermute_b32 v117, v125, v133
	ds_bpermute_b32 v118, v125, v134
	ds_bpermute_b32 v119, v125, v135
	ds_bpermute_b32 v120, v125, v136
	ds_bpermute_b32 v121, v125, v137
	ds_bpermute_b32 v122, v125, v138
	ds_bpermute_b32 v123, v125, v139
	s_waitcnt lgkmcnt(0)
	v_add_f32_e32 v130, v130, v114
	v_add_f32_e32 v131, v131, v115
	v_add_f32_e32 v132, v132, v116
	v_add_f32_e32 v133, v133, v117
	v_add_f32_e32 v134, v134, v118
	v_add_f32_e32 v135, v135, v119
	v_add_f32_e32 v136, v136, v120
	v_add_f32_e32 v137, v137, v121
	v_add_f32_e32 v138, v138, v122
	v_add_f32_e32 v139, v139, v123
	ds_bpermute_b32 v114, v126, v130
	ds_bpermute_b32 v115, v126, v131
	ds_bpermute_b32 v116, v126, v132
	ds_bpermute_b32 v117, v126, v133
	ds_bpermute_b32 v118, v126, v134
	ds_bpermute_b32 v119, v126, v135
	ds_bpermute_b32 v120, v126, v136
	ds_bpermute_b32 v121, v126, v137
	ds_bpermute_b32 v122, v126, v138
	ds_bpermute_b32 v123, v126, v139
	s_waitcnt lgkmcnt(0)
	v_add_f32_e32 v130, v130, v114
	v_add_f32_e32 v131, v131, v115
	v_add_f32_e32 v132, v132, v116
	v_add_f32_e32 v133, v133, v117
	v_add_f32_e32 v134, v134, v118
	v_add_f32_e32 v135, v135, v119
	v_add_f32_e32 v136, v136, v120
	v_add_f32_e32 v137, v137, v121
	v_add_f32_e32 v138, v138, v122
	v_add_f32_e32 v139, v139, v123
	ds_bpermute_b32 v114, v127, v130
	ds_bpermute_b32 v115, v127, v131
	ds_bpermute_b32 v116, v127, v132
	ds_bpermute_b32 v117, v127, v133
	ds_bpermute_b32 v118, v127, v134
	ds_bpermute_b32 v119, v127, v135
	ds_bpermute_b32 v120, v127, v136
	ds_bpermute_b32 v121, v127, v137
	ds_bpermute_b32 v122, v127, v138
	ds_bpermute_b32 v123, v127, v139
	s_waitcnt lgkmcnt(0)
	v_add_f32_e32 v130, v130, v114
	v_add_f32_e32 v131, v131, v115
	v_add_f32_e32 v132, v132, v116
	v_add_f32_e32 v133, v133, v117
	v_add_f32_e32 v134, v134, v118
	v_add_f32_e32 v135, v135, v119
	v_add_f32_e32 v136, v136, v120
	v_add_f32_e32 v137, v137, v121
	v_add_f32_e32 v138, v138, v122
	v_add_f32_e32 v139, v139, v123
	ds_bpermute_b32 v114, v128, v130
	ds_bpermute_b32 v115, v128, v131
	ds_bpermute_b32 v116, v128, v132
	ds_bpermute_b32 v117, v128, v133
	ds_bpermute_b32 v118, v128, v134
	ds_bpermute_b32 v119, v128, v135
	ds_bpermute_b32 v120, v128, v136
	ds_bpermute_b32 v121, v128, v137
	ds_bpermute_b32 v122, v128, v138
	ds_bpermute_b32 v123, v128, v139
	s_waitcnt lgkmcnt(0)
	v_add_f32_e32 v130, v130, v114
	v_add_f32_e32 v131, v131, v115
	v_add_f32_e32 v132, v132, v116
	v_add_f32_e32 v133, v133, v117
	v_add_f32_e32 v134, v134, v118
	v_add_f32_e32 v135, v135, v119
	v_add_f32_e32 v136, v136, v120
	v_add_f32_e32 v137, v137, v121
	v_add_f32_e32 v138, v138, v122
	v_add_f32_e32 v139, v139, v123
	ds_bpermute_b32 v114, v129, v130
	ds_bpermute_b32 v115, v129, v131
	ds_bpermute_b32 v116, v129, v132
	ds_bpermute_b32 v117, v129, v133
	ds_bpermute_b32 v118, v129, v134
	ds_bpermute_b32 v119, v129, v135
	ds_bpermute_b32 v120, v129, v136
	ds_bpermute_b32 v121, v129, v137
	ds_bpermute_b32 v122, v129, v138
	ds_bpermute_b32 v123, v129, v139
	s_waitcnt lgkmcnt(0)
	v_add_f32_e32 v130, v130, v114
	v_add_f32_e32 v131, v131, v115
	v_add_f32_e32 v132, v132, v116
	v_add_f32_e32 v133, v133, v117
	v_add_f32_e32 v134, v134, v118
	v_add_f32_e32 v135, v135, v119
	v_add_f32_e32 v136, v136, v120
	v_add_f32_e32 v137, v137, v121
	v_add_f32_e32 v138, v138, v122
	v_add_f32_e32 v139, v139, v123
	s_mov_b64 s[20:21], exec
	s_mov_b64 exec, 1
	v_mov_b32_e32 v114, 0x0
	global_store_dword v114, v130, s[24:25] offset:0
	global_store_dword v114, v135, s[24:25] offset:4
	v_mov_b32_e32 v114, 0x4200
	global_store_dword v114, v131, s[24:25] offset:0
	global_store_dword v114, v136, s[24:25] offset:4
	v_mov_b32_e32 v114, 0x8400
	global_store_dword v114, v132, s[24:25] offset:0
	global_store_dword v114, v137, s[24:25] offset:4
	v_mov_b32_e32 v114, 0xc600
	global_store_dword v114, v133, s[24:25] offset:0
	global_store_dword v114, v138, s[24:25] offset:4
	v_mov_b32_e32 v114, 0x10800
	global_store_dword v114, v134, s[24:25] offset:0
	global_store_dword v114, v139, s[24:25] offset:4
	s_mov_b64 exec, s[20:21]
	s_add_u32 s16, s16, 0x1000
	s_addc_u32 s17, s17, 0
	global_load_dwordx4 v[82:85], v141, s[16:17]
	global_load_dwordx4 v[86:89], v141, s[16:17] offset:16
	global_load_dwordx4 v[90:93], v141, s[16:17] offset:2048
	global_load_dwordx4 v[94:97], v141, s[16:17] offset:2064
	s_waitcnt vmcnt(14)
	v_lshlrev_b32_e32 v114, 16, v98
	v_and_b32_e32 v115, 0xffff0000, v98
	v_lshlrev_b32_e32 v116, 16, v99
	v_and_b32_e32 v117, 0xffff0000, v99
	v_lshlrev_b32_e32 v118, 16, v100
	v_and_b32_e32 v119, 0xffff0000, v100
	v_lshlrev_b32_e32 v120, 16, v101
	v_and_b32_e32 v121, 0xffff0000, v101
	v_lshlrev_b32_e32 v122, 16, v102
	v_and_b32_e32 v123, 0xffff0000, v102
	v_lshlrev_b32_e32 v124, 16, v103
	v_and_b32_e32 v125, 0xffff0000, v103
	v_lshlrev_b32_e32 v126, 16, v104
	v_and_b32_e32 v127, 0xffff0000, v104
	v_lshlrev_b32_e32 v128, 16, v105
	v_and_b32_e32 v129, 0xffff0000, v105
	v_fma_f32 v130, v0, v114, 0
	v_fma_f32 v131, v16, v114, 0
	v_fma_f32 v132, v32, v114, 0
	v_fma_f32 v133, v48, v114, 0
	v_fma_f32 v134, v64, v114, 0
	v_fmac_f32_e32 v130, v1, v115
	v_fmac_f32_e32 v131, v17, v115
	v_fmac_f32_e32 v132, v33, v115
	v_fmac_f32_e32 v133, v49, v115
	v_fmac_f32_e32 v134, v65, v115
	v_fmac_f32_e32 v130, v2, v116
	v_fmac_f32_e32 v131, v18, v116
	v_fmac_f32_e32 v132, v34, v116
	v_fmac_f32_e32 v133, v50, v116
	v_fmac_f32_e32 v134, v66, v116
	v_fmac_f32_e32 v130, v3, v117
	v_fmac_f32_e32 v131, v19, v117
	v_fmac_f32_e32 v132, v35, v117
	v_fmac_f32_e32 v133, v51, v117
	v_fmac_f32_e32 v134, v67, v117
	v_fmac_f32_e32 v130, v4, v118
	v_fmac_f32_e32 v131, v20, v118
	v_fmac_f32_e32 v132, v36, v118
	v_fmac_f32_e32 v133, v52, v118
	v_fmac_f32_e32 v134, v68, v118
	v_fmac_f32_e32 v130, v5, v119
	v_fmac_f32_e32 v131, v21, v119
	v_fmac_f32_e32 v132, v37, v119
	v_fmac_f32_e32 v133, v53, v119
	v_fmac_f32_e32 v134, v69, v119
	v_fmac_f32_e32 v130, v6, v120
	v_fmac_f32_e32 v131, v22, v120
	v_fmac_f32_e32 v132, v38, v120
	v_fmac_f32_e32 v133, v54, v120
	v_fmac_f32_e32 v134, v70, v120
	v_fmac_f32_e32 v130, v7, v121
	v_fmac_f32_e32 v131, v23, v121
	v_fmac_f32_e32 v132, v39, v121
	v_fmac_f32_e32 v133, v55, v121
	v_fmac_f32_e32 v134, v71, v121
	v_fmac_f32_e32 v130, v8, v122
	v_fmac_f32_e32 v131, v24, v122
	v_fmac_f32_e32 v132, v40, v122
	v_fmac_f32_e32 v133, v56, v122
	v_fmac_f32_e32 v134, v72, v122
	v_fmac_f32_e32 v130, v9, v123
	v_fmac_f32_e32 v131, v25, v123
	v_fmac_f32_e32 v132, v41, v123
	v_fmac_f32_e32 v133, v57, v123
	v_fmac_f32_e32 v134, v73, v123
	v_fmac_f32_e32 v130, v10, v124
	v_fmac_f32_e32 v131, v26, v124
	v_fmac_f32_e32 v132, v42, v124
	v_fmac_f32_e32 v133, v58, v124
	v_fmac_f32_e32 v134, v74, v124
	v_fmac_f32_e32 v130, v11, v125
	v_fmac_f32_e32 v131, v27, v125
	v_fmac_f32_e32 v132, v43, v125
	v_fmac_f32_e32 v133, v59, v125
	v_fmac_f32_e32 v134, v75, v125
	v_fmac_f32_e32 v130, v12, v126
	v_fmac_f32_e32 v131, v28, v126
	v_fmac_f32_e32 v132, v44, v126
	v_fmac_f32_e32 v133, v60, v126
	v_fmac_f32_e32 v134, v76, v126
	v_fmac_f32_e32 v130, v13, v127
	v_fmac_f32_e32 v131, v29, v127
	v_fmac_f32_e32 v132, v45, v127
	v_fmac_f32_e32 v133, v61, v127
	v_fmac_f32_e32 v134, v77, v127
	v_fmac_f32_e32 v130, v14, v128
	v_fmac_f32_e32 v131, v30, v128
	v_fmac_f32_e32 v132, v46, v128
	v_fmac_f32_e32 v133, v62, v128
	v_fmac_f32_e32 v134, v78, v128
	v_fmac_f32_e32 v130, v15, v129
	v_fmac_f32_e32 v131, v31, v129
	v_fmac_f32_e32 v132, v47, v129
	v_fmac_f32_e32 v133, v63, v129
	v_fmac_f32_e32 v134, v79, v129
	v_lshlrev_b32_e32 v114, 16, v106
	v_and_b32_e32 v115, 0xffff0000, v106
	v_lshlrev_b32_e32 v116, 16, v107
	v_and_b32_e32 v117, 0xffff0000, v107
	v_lshlrev_b32_e32 v118, 16, v108
	v_and_b32_e32 v119, 0xffff0000, v108
	v_lshlrev_b32_e32 v120, 16, v109
	v_and_b32_e32 v121, 0xffff0000, v109
	v_lshlrev_b32_e32 v122, 16, v110
	v_and_b32_e32 v123, 0xffff0000, v110
	v_lshlrev_b32_e32 v124, 16, v111
	v_and_b32_e32 v125, 0xffff0000, v111
	v_lshlrev_b32_e32 v126, 16, v112
	v_and_b32_e32 v127, 0xffff0000, v112
	v_lshlrev_b32_e32 v128, 16, v113
	v_and_b32_e32 v129, 0xffff0000, v113
	v_fma_f32 v135, v0, v114, 0
	v_fma_f32 v136, v16, v114, 0
	v_fma_f32 v137, v32, v114, 0
	v_fma_f32 v138, v48, v114, 0
	v_fma_f32 v139, v64, v114, 0
	v_fmac_f32_e32 v135, v1, v115
	v_fmac_f32_e32 v136, v17, v115
	v_fmac_f32_e32 v137, v33, v115
	v_fmac_f32_e32 v138, v49, v115
	v_fmac_f32_e32 v139, v65, v115
	v_fmac_f32_e32 v135, v2, v116
	v_fmac_f32_e32 v136, v18, v116
	v_fmac_f32_e32 v137, v34, v116
	v_fmac_f32_e32 v138, v50, v116
	v_fmac_f32_e32 v139, v66, v116
	v_fmac_f32_e32 v135, v3, v117
	v_fmac_f32_e32 v136, v19, v117
	v_fmac_f32_e32 v137, v35, v117
	v_fmac_f32_e32 v138, v51, v117
	v_fmac_f32_e32 v139, v67, v117
	v_fmac_f32_e32 v135, v4, v118
	v_fmac_f32_e32 v136, v20, v118
	v_fmac_f32_e32 v137, v36, v118
	v_fmac_f32_e32 v138, v52, v118
	v_fmac_f32_e32 v139, v68, v118
	v_fmac_f32_e32 v135, v5, v119
	v_fmac_f32_e32 v136, v21, v119
	v_fmac_f32_e32 v137, v37, v119
	v_fmac_f32_e32 v138, v53, v119
	v_fmac_f32_e32 v139, v69, v119
	v_fmac_f32_e32 v135, v6, v120
	v_fmac_f32_e32 v136, v22, v120
	v_fmac_f32_e32 v137, v38, v120
	v_fmac_f32_e32 v138, v54, v120
	v_fmac_f32_e32 v139, v70, v120
	v_fmac_f32_e32 v135, v7, v121
	v_fmac_f32_e32 v136, v23, v121
	v_fmac_f32_e32 v137, v39, v121
	v_fmac_f32_e32 v138, v55, v121
	v_fmac_f32_e32 v139, v71, v121
	v_fmac_f32_e32 v135, v8, v122
	v_fmac_f32_e32 v136, v24, v122
	v_fmac_f32_e32 v137, v40, v122
	v_fmac_f32_e32 v138, v56, v122
	v_fmac_f32_e32 v139, v72, v122
	v_fmac_f32_e32 v135, v9, v123
	v_fmac_f32_e32 v136, v25, v123
	v_fmac_f32_e32 v137, v41, v123
	v_fmac_f32_e32 v138, v57, v123
	v_fmac_f32_e32 v139, v73, v123
	v_fmac_f32_e32 v135, v10, v124
	v_fmac_f32_e32 v136, v26, v124
	v_fmac_f32_e32 v137, v42, v124
	v_fmac_f32_e32 v138, v58, v124
	v_fmac_f32_e32 v139, v74, v124
	v_fmac_f32_e32 v135, v11, v125
	v_fmac_f32_e32 v136, v27, v125
	v_fmac_f32_e32 v137, v43, v125
	v_fmac_f32_e32 v138, v59, v125
	v_fmac_f32_e32 v139, v75, v125
	v_fmac_f32_e32 v135, v12, v126
	v_fmac_f32_e32 v136, v28, v126
	v_fmac_f32_e32 v137, v44, v126
	v_fmac_f32_e32 v138, v60, v126
	v_fmac_f32_e32 v139, v76, v126
	v_fmac_f32_e32 v135, v13, v127
	v_fmac_f32_e32 v136, v29, v127
	v_fmac_f32_e32 v137, v45, v127
	v_fmac_f32_e32 v138, v61, v127
	v_fmac_f32_e32 v139, v77, v127
	v_fmac_f32_e32 v135, v14, v128
	v_fmac_f32_e32 v136, v30, v128
	v_fmac_f32_e32 v137, v46, v128
	v_fmac_f32_e32 v138, v62, v128
	v_fmac_f32_e32 v139, v78, v128
	v_fmac_f32_e32 v135, v15, v129
	v_fmac_f32_e32 v136, v31, v129
	v_fmac_f32_e32 v137, v47, v129
	v_fmac_f32_e32 v138, v63, v129
	v_fmac_f32_e32 v139, v79, v129
	v_xor_b32_e32 v124, 32, v140
	v_lshlrev_b32_e32 v124, 2, v124
	v_xor_b32_e32 v125, 16, v140
	v_lshlrev_b32_e32 v125, 2, v125
	v_xor_b32_e32 v126, 8, v140
	v_lshlrev_b32_e32 v126, 2, v126
	v_xor_b32_e32 v127, 4, v140
	v_lshlrev_b32_e32 v127, 2, v127
	v_xor_b32_e32 v128, 2, v140
	v_lshlrev_b32_e32 v128, 2, v128
	v_xor_b32_e32 v129, 1, v140
	v_lshlrev_b32_e32 v129, 2, v129
	ds_bpermute_b32 v114, v124, v130
	ds_bpermute_b32 v115, v124, v131
	ds_bpermute_b32 v116, v124, v132
	ds_bpermute_b32 v117, v124, v133
	ds_bpermute_b32 v118, v124, v134
	ds_bpermute_b32 v119, v124, v135
	ds_bpermute_b32 v120, v124, v136
	ds_bpermute_b32 v121, v124, v137
	ds_bpermute_b32 v122, v124, v138
	ds_bpermute_b32 v123, v124, v139
	s_waitcnt lgkmcnt(0)
	v_add_f32_e32 v130, v130, v114
	v_add_f32_e32 v131, v131, v115
	v_add_f32_e32 v132, v132, v116
	v_add_f32_e32 v133, v133, v117
	v_add_f32_e32 v134, v134, v118
	v_add_f32_e32 v135, v135, v119
	v_add_f32_e32 v136, v136, v120
	v_add_f32_e32 v137, v137, v121
	v_add_f32_e32 v138, v138, v122
	v_add_f32_e32 v139, v139, v123
	ds_bpermute_b32 v114, v125, v130
	ds_bpermute_b32 v115, v125, v131
	ds_bpermute_b32 v116, v125, v132
	ds_bpermute_b32 v117, v125, v133
	ds_bpermute_b32 v118, v125, v134
	ds_bpermute_b32 v119, v125, v135
	ds_bpermute_b32 v120, v125, v136
	ds_bpermute_b32 v121, v125, v137
	ds_bpermute_b32 v122, v125, v138
	ds_bpermute_b32 v123, v125, v139
	s_waitcnt lgkmcnt(0)
	v_add_f32_e32 v130, v130, v114
	v_add_f32_e32 v131, v131, v115
	v_add_f32_e32 v132, v132, v116
	v_add_f32_e32 v133, v133, v117
	v_add_f32_e32 v134, v134, v118
	v_add_f32_e32 v135, v135, v119
	v_add_f32_e32 v136, v136, v120
	v_add_f32_e32 v137, v137, v121
	v_add_f32_e32 v138, v138, v122
	v_add_f32_e32 v139, v139, v123
	ds_bpermute_b32 v114, v126, v130
	ds_bpermute_b32 v115, v126, v131
	ds_bpermute_b32 v116, v126, v132
	ds_bpermute_b32 v117, v126, v133
	ds_bpermute_b32 v118, v126, v134
	ds_bpermute_b32 v119, v126, v135
	ds_bpermute_b32 v120, v126, v136
	ds_bpermute_b32 v121, v126, v137
	ds_bpermute_b32 v122, v126, v138
	ds_bpermute_b32 v123, v126, v139
	s_waitcnt lgkmcnt(0)
	v_add_f32_e32 v130, v130, v114
	v_add_f32_e32 v131, v131, v115
	v_add_f32_e32 v132, v132, v116
	v_add_f32_e32 v133, v133, v117
	v_add_f32_e32 v134, v134, v118
	v_add_f32_e32 v135, v135, v119
	v_add_f32_e32 v136, v136, v120
	v_add_f32_e32 v137, v137, v121
	v_add_f32_e32 v138, v138, v122
	v_add_f32_e32 v139, v139, v123
	ds_bpermute_b32 v114, v127, v130
	ds_bpermute_b32 v115, v127, v131
	ds_bpermute_b32 v116, v127, v132
	ds_bpermute_b32 v117, v127, v133
	ds_bpermute_b32 v118, v127, v134
	ds_bpermute_b32 v119, v127, v135
	ds_bpermute_b32 v120, v127, v136
	ds_bpermute_b32 v121, v127, v137
	ds_bpermute_b32 v122, v127, v138
	ds_bpermute_b32 v123, v127, v139
	s_waitcnt lgkmcnt(0)
	v_add_f32_e32 v130, v130, v114
	v_add_f32_e32 v131, v131, v115
	v_add_f32_e32 v132, v132, v116
	v_add_f32_e32 v133, v133, v117
	v_add_f32_e32 v134, v134, v118
	v_add_f32_e32 v135, v135, v119
	v_add_f32_e32 v136, v136, v120
	v_add_f32_e32 v137, v137, v121
	v_add_f32_e32 v138, v138, v122
	v_add_f32_e32 v139, v139, v123
	ds_bpermute_b32 v114, v128, v130
	ds_bpermute_b32 v115, v128, v131
	ds_bpermute_b32 v116, v128, v132
	ds_bpermute_b32 v117, v128, v133
	ds_bpermute_b32 v118, v128, v134
	ds_bpermute_b32 v119, v128, v135
	ds_bpermute_b32 v120, v128, v136
	ds_bpermute_b32 v121, v128, v137
	ds_bpermute_b32 v122, v128, v138
	ds_bpermute_b32 v123, v128, v139
	s_waitcnt lgkmcnt(0)
	v_add_f32_e32 v130, v130, v114
	v_add_f32_e32 v131, v131, v115
	v_add_f32_e32 v132, v132, v116
	v_add_f32_e32 v133, v133, v117
	v_add_f32_e32 v134, v134, v118
	v_add_f32_e32 v135, v135, v119
	v_add_f32_e32 v136, v136, v120
	v_add_f32_e32 v137, v137, v121
	v_add_f32_e32 v138, v138, v122
	v_add_f32_e32 v139, v139, v123
	ds_bpermute_b32 v114, v129, v130
	ds_bpermute_b32 v115, v129, v131
	ds_bpermute_b32 v116, v129, v132
	ds_bpermute_b32 v117, v129, v133
	ds_bpermute_b32 v118, v129, v134
	ds_bpermute_b32 v119, v129, v135
	ds_bpermute_b32 v120, v129, v136
	ds_bpermute_b32 v121, v129, v137
	ds_bpermute_b32 v122, v129, v138
	ds_bpermute_b32 v123, v129, v139
	s_waitcnt lgkmcnt(0)
	v_add_f32_e32 v130, v130, v114
	v_add_f32_e32 v131, v131, v115
	v_add_f32_e32 v132, v132, v116
	v_add_f32_e32 v133, v133, v117
	v_add_f32_e32 v134, v134, v118
	v_add_f32_e32 v135, v135, v119
	v_add_f32_e32 v136, v136, v120
	v_add_f32_e32 v137, v137, v121
	v_add_f32_e32 v138, v138, v122
	v_add_f32_e32 v139, v139, v123
	s_mov_b64 s[20:21], exec
	s_mov_b64 exec, 1
	v_mov_b32_e32 v114, 0x0
	global_store_dword v114, v130, s[24:25] offset:8
	global_store_dword v114, v135, s[24:25] offset:12
	v_mov_b32_e32 v114, 0x4200
	global_store_dword v114, v131, s[24:25] offset:8
	global_store_dword v114, v136, s[24:25] offset:12
	v_mov_b32_e32 v114, 0x8400
	global_store_dword v114, v132, s[24:25] offset:8
	global_store_dword v114, v137, s[24:25] offset:12
	v_mov_b32_e32 v114, 0xc600
	global_store_dword v114, v133, s[24:25] offset:8
	global_store_dword v114, v138, s[24:25] offset:12
	v_mov_b32_e32 v114, 0x10800
	global_store_dword v114, v134, s[24:25] offset:8
	global_store_dword v114, v139, s[24:25] offset:12
	s_mov_b64 exec, s[20:21]
	s_add_u32 s16, s16, 0x1000
	s_addc_u32 s17, s17, 0
	global_load_dwordx4 v[98:101], v141, s[16:17]
	global_load_dwordx4 v[102:105], v141, s[16:17] offset:16
	global_load_dwordx4 v[106:109], v141, s[16:17] offset:2048
	global_load_dwordx4 v[110:113], v141, s[16:17] offset:2064
	s_waitcnt vmcnt(14)
	v_lshlrev_b32_e32 v114, 16, v82
	v_and_b32_e32 v115, 0xffff0000, v82
	v_lshlrev_b32_e32 v116, 16, v83
	v_and_b32_e32 v117, 0xffff0000, v83
	v_lshlrev_b32_e32 v118, 16, v84
	v_and_b32_e32 v119, 0xffff0000, v84
	v_lshlrev_b32_e32 v120, 16, v85
	v_and_b32_e32 v121, 0xffff0000, v85
	v_lshlrev_b32_e32 v122, 16, v86
	v_and_b32_e32 v123, 0xffff0000, v86
	v_lshlrev_b32_e32 v124, 16, v87
	v_and_b32_e32 v125, 0xffff0000, v87
	v_lshlrev_b32_e32 v126, 16, v88
	v_and_b32_e32 v127, 0xffff0000, v88
	v_lshlrev_b32_e32 v128, 16, v89
	v_and_b32_e32 v129, 0xffff0000, v89
	v_fma_f32 v130, v0, v114, 0
	v_fma_f32 v131, v16, v114, 0
	v_fma_f32 v132, v32, v114, 0
	v_fma_f32 v133, v48, v114, 0
	v_fma_f32 v134, v64, v114, 0
	v_fmac_f32_e32 v130, v1, v115
	v_fmac_f32_e32 v131, v17, v115
	v_fmac_f32_e32 v132, v33, v115
	v_fmac_f32_e32 v133, v49, v115
	v_fmac_f32_e32 v134, v65, v115
	v_fmac_f32_e32 v130, v2, v116
	v_fmac_f32_e32 v131, v18, v116
	v_fmac_f32_e32 v132, v34, v116
	v_fmac_f32_e32 v133, v50, v116
	v_fmac_f32_e32 v134, v66, v116
	v_fmac_f32_e32 v130, v3, v117
	v_fmac_f32_e32 v131, v19, v117
	v_fmac_f32_e32 v132, v35, v117
	v_fmac_f32_e32 v133, v51, v117
	v_fmac_f32_e32 v134, v67, v117
	v_fmac_f32_e32 v130, v4, v118
	v_fmac_f32_e32 v131, v20, v118
	v_fmac_f32_e32 v132, v36, v118
	v_fmac_f32_e32 v133, v52, v118
	v_fmac_f32_e32 v134, v68, v118
	v_fmac_f32_e32 v130, v5, v119
	v_fmac_f32_e32 v131, v21, v119
	v_fmac_f32_e32 v132, v37, v119
	v_fmac_f32_e32 v133, v53, v119
	v_fmac_f32_e32 v134, v69, v119
	v_fmac_f32_e32 v130, v6, v120
	v_fmac_f32_e32 v131, v22, v120
	v_fmac_f32_e32 v132, v38, v120
	v_fmac_f32_e32 v133, v54, v120
	v_fmac_f32_e32 v134, v70, v120
	v_fmac_f32_e32 v130, v7, v121
	v_fmac_f32_e32 v131, v23, v121
	v_fmac_f32_e32 v132, v39, v121
	v_fmac_f32_e32 v133, v55, v121
	v_fmac_f32_e32 v134, v71, v121
	v_fmac_f32_e32 v130, v8, v122
	v_fmac_f32_e32 v131, v24, v122
	v_fmac_f32_e32 v132, v40, v122
	v_fmac_f32_e32 v133, v56, v122
	v_fmac_f32_e32 v134, v72, v122
	v_fmac_f32_e32 v130, v9, v123
	v_fmac_f32_e32 v131, v25, v123
	v_fmac_f32_e32 v132, v41, v123
	v_fmac_f32_e32 v133, v57, v123
	v_fmac_f32_e32 v134, v73, v123
	v_fmac_f32_e32 v130, v10, v124
	v_fmac_f32_e32 v131, v26, v124
	v_fmac_f32_e32 v132, v42, v124
	v_fmac_f32_e32 v133, v58, v124
	v_fmac_f32_e32 v134, v74, v124
	v_fmac_f32_e32 v130, v11, v125
	v_fmac_f32_e32 v131, v27, v125
	v_fmac_f32_e32 v132, v43, v125
	v_fmac_f32_e32 v133, v59, v125
	v_fmac_f32_e32 v134, v75, v125
	v_fmac_f32_e32 v130, v12, v126
	v_fmac_f32_e32 v131, v28, v126
	v_fmac_f32_e32 v132, v44, v126
	v_fmac_f32_e32 v133, v60, v126
	v_fmac_f32_e32 v134, v76, v126
	v_fmac_f32_e32 v130, v13, v127
	v_fmac_f32_e32 v131, v29, v127
	v_fmac_f32_e32 v132, v45, v127
	v_fmac_f32_e32 v133, v61, v127
	v_fmac_f32_e32 v134, v77, v127
	v_fmac_f32_e32 v130, v14, v128
	v_fmac_f32_e32 v131, v30, v128
	v_fmac_f32_e32 v132, v46, v128
	v_fmac_f32_e32 v133, v62, v128
	v_fmac_f32_e32 v134, v78, v128
	v_fmac_f32_e32 v130, v15, v129
	v_fmac_f32_e32 v131, v31, v129
	v_fmac_f32_e32 v132, v47, v129
	v_fmac_f32_e32 v133, v63, v129
	v_fmac_f32_e32 v134, v79, v129
	v_lshlrev_b32_e32 v114, 16, v90
	v_and_b32_e32 v115, 0xffff0000, v90
	v_lshlrev_b32_e32 v116, 16, v91
	v_and_b32_e32 v117, 0xffff0000, v91
	v_lshlrev_b32_e32 v118, 16, v92
	v_and_b32_e32 v119, 0xffff0000, v92
	v_lshlrev_b32_e32 v120, 16, v93
	v_and_b32_e32 v121, 0xffff0000, v93
	v_lshlrev_b32_e32 v122, 16, v94
	v_and_b32_e32 v123, 0xffff0000, v94
	v_lshlrev_b32_e32 v124, 16, v95
	v_and_b32_e32 v125, 0xffff0000, v95
	v_lshlrev_b32_e32 v126, 16, v96
	v_and_b32_e32 v127, 0xffff0000, v96
	v_lshlrev_b32_e32 v128, 16, v97
	v_and_b32_e32 v129, 0xffff0000, v97
	v_fma_f32 v135, v0, v114, 0
	v_fma_f32 v136, v16, v114, 0
	v_fma_f32 v137, v32, v114, 0
	v_fma_f32 v138, v48, v114, 0
	v_fma_f32 v139, v64, v114, 0
	v_fmac_f32_e32 v135, v1, v115
	v_fmac_f32_e32 v136, v17, v115
	v_fmac_f32_e32 v137, v33, v115
	v_fmac_f32_e32 v138, v49, v115
	v_fmac_f32_e32 v139, v65, v115
	v_fmac_f32_e32 v135, v2, v116
	v_fmac_f32_e32 v136, v18, v116
	v_fmac_f32_e32 v137, v34, v116
	v_fmac_f32_e32 v138, v50, v116
	v_fmac_f32_e32 v139, v66, v116
	v_fmac_f32_e32 v135, v3, v117
	v_fmac_f32_e32 v136, v19, v117
	v_fmac_f32_e32 v137, v35, v117
	v_fmac_f32_e32 v138, v51, v117
	v_fmac_f32_e32 v139, v67, v117
	v_fmac_f32_e32 v135, v4, v118
	v_fmac_f32_e32 v136, v20, v118
	v_fmac_f32_e32 v137, v36, v118
	v_fmac_f32_e32 v138, v52, v118
	v_fmac_f32_e32 v139, v68, v118
	v_fmac_f32_e32 v135, v5, v119
	v_fmac_f32_e32 v136, v21, v119
	v_fmac_f32_e32 v137, v37, v119
	v_fmac_f32_e32 v138, v53, v119
	v_fmac_f32_e32 v139, v69, v119
	v_fmac_f32_e32 v135, v6, v120
	v_fmac_f32_e32 v136, v22, v120
	v_fmac_f32_e32 v137, v38, v120
	v_fmac_f32_e32 v138, v54, v120
	v_fmac_f32_e32 v139, v70, v120
	v_fmac_f32_e32 v135, v7, v121
	v_fmac_f32_e32 v136, v23, v121
	v_fmac_f32_e32 v137, v39, v121
	v_fmac_f32_e32 v138, v55, v121
	v_fmac_f32_e32 v139, v71, v121
	v_fmac_f32_e32 v135, v8, v122
	v_fmac_f32_e32 v136, v24, v122
	v_fmac_f32_e32 v137, v40, v122
	v_fmac_f32_e32 v138, v56, v122
	v_fmac_f32_e32 v139, v72, v122
	v_fmac_f32_e32 v135, v9, v123
	v_fmac_f32_e32 v136, v25, v123
	v_fmac_f32_e32 v137, v41, v123
	v_fmac_f32_e32 v138, v57, v123
	v_fmac_f32_e32 v139, v73, v123
	v_fmac_f32_e32 v135, v10, v124
	v_fmac_f32_e32 v136, v26, v124
	v_fmac_f32_e32 v137, v42, v124
	v_fmac_f32_e32 v138, v58, v124
	v_fmac_f32_e32 v139, v74, v124
	v_fmac_f32_e32 v135, v11, v125
	v_fmac_f32_e32 v136, v27, v125
	v_fmac_f32_e32 v137, v43, v125
	v_fmac_f32_e32 v138, v59, v125
	v_fmac_f32_e32 v139, v75, v125
	v_fmac_f32_e32 v135, v12, v126
	v_fmac_f32_e32 v136, v28, v126
	v_fmac_f32_e32 v137, v44, v126
	v_fmac_f32_e32 v138, v60, v126
	v_fmac_f32_e32 v139, v76, v126
	v_fmac_f32_e32 v135, v13, v127
	v_fmac_f32_e32 v136, v29, v127
	v_fmac_f32_e32 v137, v45, v127
	v_fmac_f32_e32 v138, v61, v127
	v_fmac_f32_e32 v139, v77, v127
	v_fmac_f32_e32 v135, v14, v128
	v_fmac_f32_e32 v136, v30, v128
	v_fmac_f32_e32 v137, v46, v128
	v_fmac_f32_e32 v138, v62, v128
	v_fmac_f32_e32 v139, v78, v128
	v_fmac_f32_e32 v135, v15, v129
	v_fmac_f32_e32 v136, v31, v129
	v_fmac_f32_e32 v137, v47, v129
	v_fmac_f32_e32 v138, v63, v129
	v_fmac_f32_e32 v139, v79, v129
	v_xor_b32_e32 v124, 32, v140
	v_lshlrev_b32_e32 v124, 2, v124
	v_xor_b32_e32 v125, 16, v140
	v_lshlrev_b32_e32 v125, 2, v125
	v_xor_b32_e32 v126, 8, v140
	v_lshlrev_b32_e32 v126, 2, v126
	v_xor_b32_e32 v127, 4, v140
	v_lshlrev_b32_e32 v127, 2, v127
	v_xor_b32_e32 v128, 2, v140
	v_lshlrev_b32_e32 v128, 2, v128
	v_xor_b32_e32 v129, 1, v140
	v_lshlrev_b32_e32 v129, 2, v129
	ds_bpermute_b32 v114, v124, v130
	ds_bpermute_b32 v115, v124, v131
	ds_bpermute_b32 v116, v124, v132
	ds_bpermute_b32 v117, v124, v133
	ds_bpermute_b32 v118, v124, v134
	ds_bpermute_b32 v119, v124, v135
	ds_bpermute_b32 v120, v124, v136
	ds_bpermute_b32 v121, v124, v137
	ds_bpermute_b32 v122, v124, v138
	ds_bpermute_b32 v123, v124, v139
	s_waitcnt lgkmcnt(0)
	v_add_f32_e32 v130, v130, v114
	v_add_f32_e32 v131, v131, v115
	v_add_f32_e32 v132, v132, v116
	v_add_f32_e32 v133, v133, v117
	v_add_f32_e32 v134, v134, v118
	v_add_f32_e32 v135, v135, v119
	v_add_f32_e32 v136, v136, v120
	v_add_f32_e32 v137, v137, v121
	v_add_f32_e32 v138, v138, v122
	v_add_f32_e32 v139, v139, v123
	ds_bpermute_b32 v114, v125, v130
	ds_bpermute_b32 v115, v125, v131
	ds_bpermute_b32 v116, v125, v132
	ds_bpermute_b32 v117, v125, v133
	ds_bpermute_b32 v118, v125, v134
	ds_bpermute_b32 v119, v125, v135
	ds_bpermute_b32 v120, v125, v136
	ds_bpermute_b32 v121, v125, v137
	ds_bpermute_b32 v122, v125, v138
	ds_bpermute_b32 v123, v125, v139
	s_waitcnt lgkmcnt(0)
	v_add_f32_e32 v130, v130, v114
	v_add_f32_e32 v131, v131, v115
	v_add_f32_e32 v132, v132, v116
	v_add_f32_e32 v133, v133, v117
	v_add_f32_e32 v134, v134, v118
	v_add_f32_e32 v135, v135, v119
	v_add_f32_e32 v136, v136, v120
	v_add_f32_e32 v137, v137, v121
	v_add_f32_e32 v138, v138, v122
	v_add_f32_e32 v139, v139, v123
	ds_bpermute_b32 v114, v126, v130
	ds_bpermute_b32 v115, v126, v131
	ds_bpermute_b32 v116, v126, v132
	ds_bpermute_b32 v117, v126, v133
	ds_bpermute_b32 v118, v126, v134
	ds_bpermute_b32 v119, v126, v135
	ds_bpermute_b32 v120, v126, v136
	ds_bpermute_b32 v121, v126, v137
	ds_bpermute_b32 v122, v126, v138
	ds_bpermute_b32 v123, v126, v139
	s_waitcnt lgkmcnt(0)
	v_add_f32_e32 v130, v130, v114
	v_add_f32_e32 v131, v131, v115
	v_add_f32_e32 v132, v132, v116
	v_add_f32_e32 v133, v133, v117
	v_add_f32_e32 v134, v134, v118
	v_add_f32_e32 v135, v135, v119
	v_add_f32_e32 v136, v136, v120
	v_add_f32_e32 v137, v137, v121
	v_add_f32_e32 v138, v138, v122
	v_add_f32_e32 v139, v139, v123
	ds_bpermute_b32 v114, v127, v130
	ds_bpermute_b32 v115, v127, v131
	ds_bpermute_b32 v116, v127, v132
	ds_bpermute_b32 v117, v127, v133
	ds_bpermute_b32 v118, v127, v134
	ds_bpermute_b32 v119, v127, v135
	ds_bpermute_b32 v120, v127, v136
	ds_bpermute_b32 v121, v127, v137
	ds_bpermute_b32 v122, v127, v138
	ds_bpermute_b32 v123, v127, v139
	s_waitcnt lgkmcnt(0)
	v_add_f32_e32 v130, v130, v114
	v_add_f32_e32 v131, v131, v115
	v_add_f32_e32 v132, v132, v116
	v_add_f32_e32 v133, v133, v117
	v_add_f32_e32 v134, v134, v118
	v_add_f32_e32 v135, v135, v119
	v_add_f32_e32 v136, v136, v120
	v_add_f32_e32 v137, v137, v121
	v_add_f32_e32 v138, v138, v122
	v_add_f32_e32 v139, v139, v123
	ds_bpermute_b32 v114, v128, v130
	ds_bpermute_b32 v115, v128, v131
	ds_bpermute_b32 v116, v128, v132
	ds_bpermute_b32 v117, v128, v133
	ds_bpermute_b32 v118, v128, v134
	ds_bpermute_b32 v119, v128, v135
	ds_bpermute_b32 v120, v128, v136
	ds_bpermute_b32 v121, v128, v137
	ds_bpermute_b32 v122, v128, v138
	ds_bpermute_b32 v123, v128, v139
	s_waitcnt lgkmcnt(0)
	v_add_f32_e32 v130, v130, v114
	v_add_f32_e32 v131, v131, v115
	v_add_f32_e32 v132, v132, v116
	v_add_f32_e32 v133, v133, v117
	v_add_f32_e32 v134, v134, v118
	v_add_f32_e32 v135, v135, v119
	v_add_f32_e32 v136, v136, v120
	v_add_f32_e32 v137, v137, v121
	v_add_f32_e32 v138, v138, v122
	v_add_f32_e32 v139, v139, v123
	ds_bpermute_b32 v114, v129, v130
	ds_bpermute_b32 v115, v129, v131
	ds_bpermute_b32 v116, v129, v132
	ds_bpermute_b32 v117, v129, v133
	ds_bpermute_b32 v118, v129, v134
	ds_bpermute_b32 v119, v129, v135
	ds_bpermute_b32 v120, v129, v136
	ds_bpermute_b32 v121, v129, v137
	ds_bpermute_b32 v122, v129, v138
	ds_bpermute_b32 v123, v129, v139
	s_waitcnt lgkmcnt(0)
	v_add_f32_e32 v130, v130, v114
	v_add_f32_e32 v131, v131, v115
	v_add_f32_e32 v132, v132, v116
	v_add_f32_e32 v133, v133, v117
	v_add_f32_e32 v134, v134, v118
	v_add_f32_e32 v135, v135, v119
	v_add_f32_e32 v136, v136, v120
	v_add_f32_e32 v137, v137, v121
	v_add_f32_e32 v138, v138, v122
	v_add_f32_e32 v139, v139, v123
	s_mov_b64 s[20:21], exec
	s_mov_b64 exec, 1
	v_mov_b32_e32 v114, 0x0
	global_store_dword v114, v130, s[24:25] offset:16
	global_store_dword v114, v135, s[24:25] offset:20
	v_mov_b32_e32 v114, 0x4200
	global_store_dword v114, v131, s[24:25] offset:16
	global_store_dword v114, v136, s[24:25] offset:20
	v_mov_b32_e32 v114, 0x8400
	global_store_dword v114, v132, s[24:25] offset:16
	global_store_dword v114, v137, s[24:25] offset:20
	v_mov_b32_e32 v114, 0xc600
	global_store_dword v114, v133, s[24:25] offset:16
	global_store_dword v114, v138, s[24:25] offset:20
	v_mov_b32_e32 v114, 0x10800
	global_store_dword v114, v134, s[24:25] offset:16
	global_store_dword v114, v139, s[24:25] offset:20
	s_mov_b64 exec, s[20:21]
	s_waitcnt vmcnt(10)
	v_lshlrev_b32_e32 v114, 16, v98
	v_and_b32_e32 v115, 0xffff0000, v98
	v_lshlrev_b32_e32 v116, 16, v99
	v_and_b32_e32 v117, 0xffff0000, v99
	v_lshlrev_b32_e32 v118, 16, v100
	v_and_b32_e32 v119, 0xffff0000, v100
	v_lshlrev_b32_e32 v120, 16, v101
	v_and_b32_e32 v121, 0xffff0000, v101
	v_lshlrev_b32_e32 v122, 16, v102
	v_and_b32_e32 v123, 0xffff0000, v102
	v_lshlrev_b32_e32 v124, 16, v103
	v_and_b32_e32 v125, 0xffff0000, v103
	v_lshlrev_b32_e32 v126, 16, v104
	v_and_b32_e32 v127, 0xffff0000, v104
	v_lshlrev_b32_e32 v128, 16, v105
	v_and_b32_e32 v129, 0xffff0000, v105
	v_fma_f32 v130, v0, v114, 0
	v_fma_f32 v131, v16, v114, 0
	v_fma_f32 v132, v32, v114, 0
	v_fma_f32 v133, v48, v114, 0
	v_fma_f32 v134, v64, v114, 0
	v_fmac_f32_e32 v130, v1, v115
	v_fmac_f32_e32 v131, v17, v115
	v_fmac_f32_e32 v132, v33, v115
	v_fmac_f32_e32 v133, v49, v115
	v_fmac_f32_e32 v134, v65, v115
	v_fmac_f32_e32 v130, v2, v116
	v_fmac_f32_e32 v131, v18, v116
	v_fmac_f32_e32 v132, v34, v116
	v_fmac_f32_e32 v133, v50, v116
	v_fmac_f32_e32 v134, v66, v116
	v_fmac_f32_e32 v130, v3, v117
	v_fmac_f32_e32 v131, v19, v117
	v_fmac_f32_e32 v132, v35, v117
	v_fmac_f32_e32 v133, v51, v117
	v_fmac_f32_e32 v134, v67, v117
	v_fmac_f32_e32 v130, v4, v118
	v_fmac_f32_e32 v131, v20, v118
	v_fmac_f32_e32 v132, v36, v118
	v_fmac_f32_e32 v133, v52, v118
	v_fmac_f32_e32 v134, v68, v118
	v_fmac_f32_e32 v130, v5, v119
	v_fmac_f32_e32 v131, v21, v119
	v_fmac_f32_e32 v132, v37, v119
	v_fmac_f32_e32 v133, v53, v119
	v_fmac_f32_e32 v134, v69, v119
	v_fmac_f32_e32 v130, v6, v120
	v_fmac_f32_e32 v131, v22, v120
	v_fmac_f32_e32 v132, v38, v120
	v_fmac_f32_e32 v133, v54, v120
	v_fmac_f32_e32 v134, v70, v120
	v_fmac_f32_e32 v130, v7, v121
	v_fmac_f32_e32 v131, v23, v121
	v_fmac_f32_e32 v132, v39, v121
	v_fmac_f32_e32 v133, v55, v121
	v_fmac_f32_e32 v134, v71, v121
	v_fmac_f32_e32 v130, v8, v122
	v_fmac_f32_e32 v131, v24, v122
	v_fmac_f32_e32 v132, v40, v122
	v_fmac_f32_e32 v133, v56, v122
	v_fmac_f32_e32 v134, v72, v122
	v_fmac_f32_e32 v130, v9, v123
	v_fmac_f32_e32 v131, v25, v123
	v_fmac_f32_e32 v132, v41, v123
	v_fmac_f32_e32 v133, v57, v123
	v_fmac_f32_e32 v134, v73, v123
	v_fmac_f32_e32 v130, v10, v124
	v_fmac_f32_e32 v131, v26, v124
	v_fmac_f32_e32 v132, v42, v124
	v_fmac_f32_e32 v133, v58, v124
	v_fmac_f32_e32 v134, v74, v124
	v_fmac_f32_e32 v130, v11, v125
	v_fmac_f32_e32 v131, v27, v125
	v_fmac_f32_e32 v132, v43, v125
	v_fmac_f32_e32 v133, v59, v125
	v_fmac_f32_e32 v134, v75, v125
	v_fmac_f32_e32 v130, v12, v126
	v_fmac_f32_e32 v131, v28, v126
	v_fmac_f32_e32 v132, v44, v126
	v_fmac_f32_e32 v133, v60, v126
	v_fmac_f32_e32 v134, v76, v126
	v_fmac_f32_e32 v130, v13, v127
	v_fmac_f32_e32 v131, v29, v127
	v_fmac_f32_e32 v132, v45, v127
	v_fmac_f32_e32 v133, v61, v127
	v_fmac_f32_e32 v134, v77, v127
	v_fmac_f32_e32 v130, v14, v128
	v_fmac_f32_e32 v131, v30, v128
	v_fmac_f32_e32 v132, v46, v128
	v_fmac_f32_e32 v133, v62, v128
	v_fmac_f32_e32 v134, v78, v128
	v_fmac_f32_e32 v130, v15, v129
	v_fmac_f32_e32 v131, v31, v129
	v_fmac_f32_e32 v132, v47, v129
	v_fmac_f32_e32 v133, v63, v129
	v_fmac_f32_e32 v134, v79, v129
	v_lshlrev_b32_e32 v114, 16, v106
	v_and_b32_e32 v115, 0xffff0000, v106
	v_lshlrev_b32_e32 v116, 16, v107
	v_and_b32_e32 v117, 0xffff0000, v107
	v_lshlrev_b32_e32 v118, 16, v108
	v_and_b32_e32 v119, 0xffff0000, v108
	v_lshlrev_b32_e32 v120, 16, v109
	v_and_b32_e32 v121, 0xffff0000, v109
	v_lshlrev_b32_e32 v122, 16, v110
	v_and_b32_e32 v123, 0xffff0000, v110
	v_lshlrev_b32_e32 v124, 16, v111
	v_and_b32_e32 v125, 0xffff0000, v111
	v_lshlrev_b32_e32 v126, 16, v112
	v_and_b32_e32 v127, 0xffff0000, v112
	v_lshlrev_b32_e32 v128, 16, v113
	v_and_b32_e32 v129, 0xffff0000, v113
	v_fma_f32 v135, v0, v114, 0
	v_fma_f32 v136, v16, v114, 0
	v_fma_f32 v137, v32, v114, 0
	v_fma_f32 v138, v48, v114, 0
	v_fma_f32 v139, v64, v114, 0
	v_fmac_f32_e32 v135, v1, v115
	v_fmac_f32_e32 v136, v17, v115
	v_fmac_f32_e32 v137, v33, v115
	v_fmac_f32_e32 v138, v49, v115
	v_fmac_f32_e32 v139, v65, v115
	v_fmac_f32_e32 v135, v2, v116
	v_fmac_f32_e32 v136, v18, v116
	v_fmac_f32_e32 v137, v34, v116
	v_fmac_f32_e32 v138, v50, v116
	v_fmac_f32_e32 v139, v66, v116
	v_fmac_f32_e32 v135, v3, v117
	v_fmac_f32_e32 v136, v19, v117
	v_fmac_f32_e32 v137, v35, v117
	v_fmac_f32_e32 v138, v51, v117
	v_fmac_f32_e32 v139, v67, v117
	v_fmac_f32_e32 v135, v4, v118
	v_fmac_f32_e32 v136, v20, v118
	v_fmac_f32_e32 v137, v36, v118
	v_fmac_f32_e32 v138, v52, v118
	v_fmac_f32_e32 v139, v68, v118
	v_fmac_f32_e32 v135, v5, v119
	v_fmac_f32_e32 v136, v21, v119
	v_fmac_f32_e32 v137, v37, v119
	v_fmac_f32_e32 v138, v53, v119
	v_fmac_f32_e32 v139, v69, v119
	v_fmac_f32_e32 v135, v6, v120
	v_fmac_f32_e32 v136, v22, v120
	v_fmac_f32_e32 v137, v38, v120
	v_fmac_f32_e32 v138, v54, v120
	v_fmac_f32_e32 v139, v70, v120
	v_fmac_f32_e32 v135, v7, v121
	v_fmac_f32_e32 v136, v23, v121
	v_fmac_f32_e32 v137, v39, v121
	v_fmac_f32_e32 v138, v55, v121
	v_fmac_f32_e32 v139, v71, v121
	v_fmac_f32_e32 v135, v8, v122
	v_fmac_f32_e32 v136, v24, v122
	v_fmac_f32_e32 v137, v40, v122
	v_fmac_f32_e32 v138, v56, v122
	v_fmac_f32_e32 v139, v72, v122
	v_fmac_f32_e32 v135, v9, v123
	v_fmac_f32_e32 v136, v25, v123
	v_fmac_f32_e32 v137, v41, v123
	v_fmac_f32_e32 v138, v57, v123
	v_fmac_f32_e32 v139, v73, v123
	v_fmac_f32_e32 v135, v10, v124
	v_fmac_f32_e32 v136, v26, v124
	v_fmac_f32_e32 v137, v42, v124
	v_fmac_f32_e32 v138, v58, v124
	v_fmac_f32_e32 v139, v74, v124
	v_fmac_f32_e32 v135, v11, v125
	v_fmac_f32_e32 v136, v27, v125
	v_fmac_f32_e32 v137, v43, v125
	v_fmac_f32_e32 v138, v59, v125
	v_fmac_f32_e32 v139, v75, v125
	v_fmac_f32_e32 v135, v12, v126
	v_fmac_f32_e32 v136, v28, v126
	v_fmac_f32_e32 v137, v44, v126
	v_fmac_f32_e32 v138, v60, v126
	v_fmac_f32_e32 v139, v76, v126
	v_fmac_f32_e32 v135, v13, v127
	v_fmac_f32_e32 v136, v29, v127
	v_fmac_f32_e32 v137, v45, v127
	v_fmac_f32_e32 v138, v61, v127
	v_fmac_f32_e32 v139, v77, v127
	v_fmac_f32_e32 v135, v14, v128
	v_fmac_f32_e32 v136, v30, v128
	v_fmac_f32_e32 v137, v46, v128
	v_fmac_f32_e32 v138, v62, v128
	v_fmac_f32_e32 v139, v78, v128
	v_fmac_f32_e32 v135, v15, v129
	v_fmac_f32_e32 v136, v31, v129
	v_fmac_f32_e32 v137, v47, v129
	v_fmac_f32_e32 v138, v63, v129
	v_fmac_f32_e32 v139, v79, v129
	v_xor_b32_e32 v124, 32, v140
	v_lshlrev_b32_e32 v124, 2, v124
	v_xor_b32_e32 v125, 16, v140
	v_lshlrev_b32_e32 v125, 2, v125
	v_xor_b32_e32 v126, 8, v140
	v_lshlrev_b32_e32 v126, 2, v126
	v_xor_b32_e32 v127, 4, v140
	v_lshlrev_b32_e32 v127, 2, v127
	v_xor_b32_e32 v128, 2, v140
	v_lshlrev_b32_e32 v128, 2, v128
	v_xor_b32_e32 v129, 1, v140
	v_lshlrev_b32_e32 v129, 2, v129
	ds_bpermute_b32 v114, v124, v130
	ds_bpermute_b32 v115, v124, v131
	ds_bpermute_b32 v116, v124, v132
	ds_bpermute_b32 v117, v124, v133
	ds_bpermute_b32 v118, v124, v134
	ds_bpermute_b32 v119, v124, v135
	ds_bpermute_b32 v120, v124, v136
	ds_bpermute_b32 v121, v124, v137
	ds_bpermute_b32 v122, v124, v138
	ds_bpermute_b32 v123, v124, v139
	s_waitcnt lgkmcnt(0)
	v_add_f32_e32 v130, v130, v114
	v_add_f32_e32 v131, v131, v115
	v_add_f32_e32 v132, v132, v116
	v_add_f32_e32 v133, v133, v117
	v_add_f32_e32 v134, v134, v118
	v_add_f32_e32 v135, v135, v119
	v_add_f32_e32 v136, v136, v120
	v_add_f32_e32 v137, v137, v121
	v_add_f32_e32 v138, v138, v122
	v_add_f32_e32 v139, v139, v123
	ds_bpermute_b32 v114, v125, v130
	ds_bpermute_b32 v115, v125, v131
	ds_bpermute_b32 v116, v125, v132
	ds_bpermute_b32 v117, v125, v133
	ds_bpermute_b32 v118, v125, v134
	ds_bpermute_b32 v119, v125, v135
	ds_bpermute_b32 v120, v125, v136
	ds_bpermute_b32 v121, v125, v137
	ds_bpermute_b32 v122, v125, v138
	ds_bpermute_b32 v123, v125, v139
	s_waitcnt lgkmcnt(0)
	v_add_f32_e32 v130, v130, v114
	v_add_f32_e32 v131, v131, v115
	v_add_f32_e32 v132, v132, v116
	v_add_f32_e32 v133, v133, v117
	v_add_f32_e32 v134, v134, v118
	v_add_f32_e32 v135, v135, v119
	v_add_f32_e32 v136, v136, v120
	v_add_f32_e32 v137, v137, v121
	v_add_f32_e32 v138, v138, v122
	v_add_f32_e32 v139, v139, v123
	ds_bpermute_b32 v114, v126, v130
	ds_bpermute_b32 v115, v126, v131
	ds_bpermute_b32 v116, v126, v132
	ds_bpermute_b32 v117, v126, v133
	ds_bpermute_b32 v118, v126, v134
	ds_bpermute_b32 v119, v126, v135
	ds_bpermute_b32 v120, v126, v136
	ds_bpermute_b32 v121, v126, v137
	ds_bpermute_b32 v122, v126, v138
	ds_bpermute_b32 v123, v126, v139
	s_waitcnt lgkmcnt(0)
	v_add_f32_e32 v130, v130, v114
	v_add_f32_e32 v131, v131, v115
	v_add_f32_e32 v132, v132, v116
	v_add_f32_e32 v133, v133, v117
	v_add_f32_e32 v134, v134, v118
	v_add_f32_e32 v135, v135, v119
	v_add_f32_e32 v136, v136, v120
	v_add_f32_e32 v137, v137, v121
	v_add_f32_e32 v138, v138, v122
	v_add_f32_e32 v139, v139, v123
	ds_bpermute_b32 v114, v127, v130
	ds_bpermute_b32 v115, v127, v131
	ds_bpermute_b32 v116, v127, v132
	ds_bpermute_b32 v117, v127, v133
	ds_bpermute_b32 v118, v127, v134
	ds_bpermute_b32 v119, v127, v135
	ds_bpermute_b32 v120, v127, v136
	ds_bpermute_b32 v121, v127, v137
	ds_bpermute_b32 v122, v127, v138
	ds_bpermute_b32 v123, v127, v139
	s_waitcnt lgkmcnt(0)
	v_add_f32_e32 v130, v130, v114
	v_add_f32_e32 v131, v131, v115
	v_add_f32_e32 v132, v132, v116
	v_add_f32_e32 v133, v133, v117
	v_add_f32_e32 v134, v134, v118
	v_add_f32_e32 v135, v135, v119
	v_add_f32_e32 v136, v136, v120
	v_add_f32_e32 v137, v137, v121
	v_add_f32_e32 v138, v138, v122
	v_add_f32_e32 v139, v139, v123
	ds_bpermute_b32 v114, v128, v130
	ds_bpermute_b32 v115, v128, v131
	ds_bpermute_b32 v116, v128, v132
	ds_bpermute_b32 v117, v128, v133
	ds_bpermute_b32 v118, v128, v134
	ds_bpermute_b32 v119, v128, v135
	ds_bpermute_b32 v120, v128, v136
	ds_bpermute_b32 v121, v128, v137
	ds_bpermute_b32 v122, v128, v138
	ds_bpermute_b32 v123, v128, v139
	s_waitcnt lgkmcnt(0)
	v_add_f32_e32 v130, v130, v114
	v_add_f32_e32 v131, v131, v115
	v_add_f32_e32 v132, v132, v116
	v_add_f32_e32 v133, v133, v117
	v_add_f32_e32 v134, v134, v118
	v_add_f32_e32 v135, v135, v119
	v_add_f32_e32 v136, v136, v120
	v_add_f32_e32 v137, v137, v121
	v_add_f32_e32 v138, v138, v122
	v_add_f32_e32 v139, v139, v123
	ds_bpermute_b32 v114, v129, v130
	ds_bpermute_b32 v115, v129, v131
	ds_bpermute_b32 v116, v129, v132
	ds_bpermute_b32 v117, v129, v133
	ds_bpermute_b32 v118, v129, v134
	ds_bpermute_b32 v119, v129, v135
	ds_bpermute_b32 v120, v129, v136
	ds_bpermute_b32 v121, v129, v137
	ds_bpermute_b32 v122, v129, v138
	ds_bpermute_b32 v123, v129, v139
	s_waitcnt lgkmcnt(0)
	v_add_f32_e32 v130, v130, v114
	v_add_f32_e32 v131, v131, v115
	v_add_f32_e32 v132, v132, v116
	v_add_f32_e32 v133, v133, v117
	v_add_f32_e32 v134, v134, v118
	v_add_f32_e32 v135, v135, v119
	v_add_f32_e32 v136, v136, v120
	v_add_f32_e32 v137, v137, v121
	v_add_f32_e32 v138, v138, v122
	v_add_f32_e32 v139, v139, v123
	s_mov_b64 s[20:21], exec
	s_mov_b64 exec, 1
	v_mov_b32_e32 v114, 0x0
	global_store_dword v114, v130, s[24:25] offset:24
	global_store_dword v114, v135, s[24:25] offset:28
	v_mov_b32_e32 v114, 0x4200
	global_store_dword v114, v131, s[24:25] offset:24
	global_store_dword v114, v136, s[24:25] offset:28
	v_mov_b32_e32 v114, 0x8400
	global_store_dword v114, v132, s[24:25] offset:24
	global_store_dword v114, v137, s[24:25] offset:28
	v_mov_b32_e32 v114, 0xc600
	global_store_dword v114, v133, s[24:25] offset:24
	global_store_dword v114, v138, s[24:25] offset:28
	v_mov_b32_e32 v114, 0x10800
	global_store_dword v114, v134, s[24:25] offset:24
	global_store_dword v114, v139, s[24:25] offset:28
	s_mov_b64 exec, s[20:21]
	s_add_i32 s1, s1, s0
	s_cmp_lt_u32 s1, 0x544
	s_cbranch_scc1 .Lsw_task
